# previous stacked version plus rownorm adaLN scale/shift loads hoisted and issued together in both rownorm loops (one L2 round trip instead of 4-7 per trip)
# baseline (speedup 1.0000x reference)
; __device__ __forceinline__ void rownorm_phase(const XBuf xin, const float* mod_shift, const float* mod_scale, bf16_t* XN, int lane, int gw, int NGW) {
;     for (int row0 = gw * 2; row0 < T; row0 += NGW * 2) {
;         const int bi = batch_of(row0);
;         float v[2][4][8]; float ss0 = 0.f, ss1 = 0.f;
; #pragma unroll
;         for (int j = 0; j < 4; ++j) { xload8(xin, row0, 8 * lane + 512 * j, v[0][j]); xload8(xin, row0 + 1, 8 * lane + 512 * j, v[1][j]); }
; #pragma unroll
;         for (int j = 0; j < 4; ++j)
; #pragma unroll
;             for (int k = 0; k < 8; ++k) { ss0 += v[0][j][k] * v[0][j][k]; ss1 += v[1][j][k] * v[1][j][k]; }
;         const float rs0 = rsqrtf(wave_sum(ss0) * (1.0f / D) + EPS), rs1 = rsqrtf(wave_sum(ss1) * (1.0f / D) + EPS);
;         const float* sh = mod_shift + (size_t)bi * NMOD; const float* sc = mod_scale + (size_t)bi * NMOD;
; #pragma unroll
;         for (int j = 0; j < 4; ++j) { const int c = 8 * lane + 512 * j;
;             const f32x4 s0 = 1.0f + *(const f32x4*)(sc + c), s1 = 1.0f + *(const f32x4*)(sc + c + 4), h0 = *(const f32x4*)(sh + c), h1 = *(const f32x4*)(sh + c + 4);
.LBB0_514:
	s_add_i32 s0, s6, 0xffff8000
	s_lshr_b32 s0, s0, 6
	s_add_i32 s7, s0, 2
	s_cmp_lt_i32 s6, s28
	s_cselect_b32 s0, s30, s33
	s_cselect_b32 s1, s29, s31
	s_add_i32 s9, s6, 1
	s_cmp_lt_i32 s9, s28
	s_cselect_b32 s12, s30, s33
	s_cselect_b32 s13, s29, s31
	s_ashr_i32 s9, s6, 14
	s_cmp_lt_i32 s6, 0x8000
	v_lshl_add_u64 v[0:1], s[0:1], 0, v[34:35]
	s_cselect_b32 s0, s9, s7
	s_mul_hi_i32 s1, s0, 0xc000
	s_mul_i32 s0, s0, 0xc000
	v_lshl_add_u64 v[2:3], s[12:13], 0, v[34:35]
	s_add_u32 s12, s2, s0
	s_addc_u32 s13, s3, s1
	v_add_co_u32_e32 v2, vcc, s86, v2
	s_add_u32 s14, s16, s0
	s_nop 0
	v_addc_co_u32_e32 v3, vcc, 0, v3, vcc
	s_addc_u32 s15, s17, s1
	global_load_dwordx4 v[36:39], v[0:1], off
	global_load_dwordx4 v[40:43], v[2:3], off
	global_load_dwordx4 v[26:29], v[0:1], off offset:1024
	global_load_dwordx4 v[30:33], v[2:3], off offset:1024
	global_load_dwordx4 v[18:21], v[0:1], off offset:2048
	global_load_dwordx4 v[22:25], v[2:3], off offset:2048
	global_load_dwordx4 v[10:13], v[0:1], off offset:3072
	global_load_dwordx4 v[14:17], v[2:3], off offset:3072
	s_nop 0
	global_load_dwordx4 v[2:5], v98, s[14:15] offset:16
	global_load_dwordx4 v[6:9], v98, s[14:15]
	global_load_dwordx4 v[116:119], v98, s[12:13] offset:16
	global_load_dwordx4 v[120:123], v98, s[12:13]
	global_load_dwordx4 v[124:127], v98, s[14:15] offset:2064
	global_load_dwordx4 v[128:131], v98, s[14:15] offset:2048
	global_load_dwordx4 v[132:135], v98, s[12:13] offset:2064
	global_load_dwordx4 v[136:139], v98, s[12:13] offset:2048
	global_load_dwordx4 v[140:143], v99, s[14:15] offset:16
	global_load_dwordx4 v[144:147], v99, s[14:15]
	global_load_dwordx4 v[148:151], v99, s[12:13] offset:16
	global_load_dwordx4 v[152:155], v99, s[12:13]
	global_load_dwordx4 v[156:159], v100, s[14:15] offset:16
	global_load_dwordx4 v[168:171], v100, s[14:15]
	global_load_dwordx4 v[172:175], v100, s[12:13] offset:16
	global_load_dwordx4 v[176:179], v100, s[12:13]
	v_lshl_add_u64 v[66:67], s[20:21], 0, v[34:35]
	s_add_i32 s6, s6, s8
	v_lshl_add_u64 v[34:35], v[34:35], 0, s[10:11]
	s_cmp_gt_i32 s6, 0x87ff
	s_waitcnt vmcnt(0)
	v_and_b32_e32 v63, 0xffff0000, v40
	v_lshlrev_b32_e32 v62, 16, v40
	v_mov_b32_e32 v50, v63
	v_lshlrev_b32_e32 v60, 16, v41
	v_mov_b32_e32 v46, v62
	v_and_b32_e32 v81, 0xffff0000, v36
	v_pk_add_f32 v[68:69], v[4:5], 1.0 op_sel_hi:[1,0]
	v_pk_add_f32 v[70:71], v[8:9], 1.0 op_sel_hi:[1,0]
	v_pk_add_f32 v[0:1], v[6:7], 1.0 op_sel_hi:[1,0]
	v_pk_add_f32 v[72:73], v[2:3], 1.0 op_sel_hi:[1,0]
	v_mov_b32_e32 v2, v116
	v_mov_b32_e32 v3, v117
	v_mov_b32_e32 v4, v118
	v_mov_b32_e32 v5, v119
	v_mov_b32_e32 v6, v120
	v_mov_b32_e32 v7, v121
	v_mov_b32_e32 v8, v122
	v_mov_b32_e32 v9, v123
	v_lshlrev_b32_e32 v80, 16, v36
	v_mov_b32_e32 v51, v81
	v_lshlrev_b32_e32 v78, 16, v37
	v_mov_b32_e32 v47, v80
	v_pk_mul_f32 v[50:51], v[50:51], v[50:51]
	v_and_b32_e32 v79, 0xffff0000, v37
	v_lshlrev_b32_e32 v56, 16, v43
	v_and_b32_e32 v57, 0xffff0000, v43
	v_lshlrev_b32_e32 v58, 16, v42
	v_and_b32_e32 v59, 0xffff0000, v42
	v_and_b32_e32 v61, 0xffff0000, v41
	v_mov_b32_e32 v42, v60
	v_mov_b32_e32 v43, v78
	v_pk_fma_f32 v[46:47], v[46:47], v[46:47], v[50:51]
	v_lshlrev_b32_e32 v76, 16, v38
	v_mov_b32_e32 v44, v61
	v_mov_b32_e32 v45, v79
	v_pk_fma_f32 v[42:43], v[42:43], v[42:43], v[46:47]
	v_lshlrev_b32_e32 v74, 16, v39
	v_and_b32_e32 v75, 0xffff0000, v39
	v_and_b32_e32 v77, 0xffff0000, v38
	v_mov_b32_e32 v38, v58
	v_mov_b32_e32 v39, v76
	v_pk_fma_f32 v[42:43], v[44:45], v[44:45], v[42:43]
	v_mov_b32_e32 v40, v59
	v_mov_b32_e32 v41, v77
	v_pk_fma_f32 v[38:39], v[38:39], v[38:39], v[42:43]
	v_mov_b32_e32 v36, v56
	v_mov_b32_e32 v37, v74
	v_pk_fma_f32 v[38:39], v[40:41], v[40:41], v[38:39]
	v_mov_b32_e32 v48, v57
	v_mov_b32_e32 v49, v75
	v_pk_fma_f32 v[50:51], v[36:37], v[36:37], v[38:39]
	v_lshlrev_b32_e32 v86, 16, v30
	v_lshlrev_b32_e32 v38, 16, v26
	v_and_b32_e32 v87, 0xffff0000, v30
	v_and_b32_e32 v39, 0xffff0000, v26
	v_lshlrev_b32_e32 v44, 16, v19
	v_and_b32_e32 v45, 0xffff0000, v19
	v_lshlrev_b32_e32 v46, 16, v18
	v_and_b32_e32 v47, 0xffff0000, v18
	v_pk_fma_f32 v[18:19], v[48:49], v[48:49], v[50:51]
	v_mov_b32_e32 v102, v86
	v_mov_b32_e32 v103, v38
	v_lshlrev_b32_e32 v84, 16, v31
	v_lshlrev_b32_e32 v36, 16, v27
	v_mov_b32_e32 v104, v87
	v_mov_b32_e32 v105, v39
	v_pk_fma_f32 v[18:19], v[102:103], v[102:103], v[18:19]
	v_and_b32_e32 v85, 0xffff0000, v31
	v_and_b32_e32 v37, 0xffff0000, v27
	v_mov_b32_e32 v52, v84
	v_mov_b32_e32 v53, v36
	v_pk_fma_f32 v[18:19], v[104:105], v[104:105], v[18:19]
	v_lshlrev_b32_e32 v82, 16, v32
	v_and_b32_e32 v83, 0xffff0000, v32
	v_lshlrev_b32_e32 v32, 16, v28
	v_mov_b32_e32 v54, v85
	v_mov_b32_e32 v55, v37
	v_pk_fma_f32 v[18:19], v[52:53], v[52:53], v[18:19]
	v_lshlrev_b32_e32 v64, 16, v33
	v_and_b32_e32 v65, 0xffff0000, v33
	v_and_b32_e32 v33, 0xffff0000, v28
	v_mov_b32_e32 v48, v82
	v_mov_b32_e32 v49, v32
	v_pk_fma_f32 v[18:19], v[54:55], v[54:55], v[18:19]
	v_lshlrev_b32_e32 v30, 16, v29
	v_mov_b32_e32 v50, v83
	v_mov_b32_e32 v51, v33
	v_pk_fma_f32 v[18:19], v[48:49], v[48:49], v[18:19]
	v_and_b32_e32 v31, 0xffff0000, v29
	v_lshlrev_b32_e32 v40, 16, v21
	v_and_b32_e32 v41, 0xffff0000, v21
	v_lshlrev_b32_e32 v42, 16, v20
	v_and_b32_e32 v43, 0xffff0000, v20
	v_mov_b32_e32 v20, v64
	v_mov_b32_e32 v21, v30
	v_pk_fma_f32 v[18:19], v[50:51], v[50:51], v[18:19]
	v_lshlrev_b32_e32 v88, 16, v25
	v_and_b32_e32 v89, 0xffff0000, v25
	v_lshlrev_b32_e32 v90, 16, v24
	v_and_b32_e32 v91, 0xffff0000, v24
	v_lshlrev_b32_e32 v24, 16, v23
	v_and_b32_e32 v25, 0xffff0000, v23
	v_lshlrev_b32_e32 v26, 16, v22
	v_and_b32_e32 v27, 0xffff0000, v22
	v_mov_b32_e32 v22, v65
	v_mov_b32_e32 v23, v31
; __device__ __forceinline__ unsigned pk2(float lo, float hi) { const f32x2 v = {lo, hi}; return __builtin_bit_cast(unsigned, __builtin_convertvector(v, bf16x2_t)); }
; __device__ __forceinline__ void rownorm_phase(const XBuf xin, const float* mod_shift, const float* mod_scale, bf16_t* XN, int lane, int gw, int NGW) {
;     ...
;         for (int j = 0; j < 4; ++j)
; #pragma unroll
;             for (int k = 0; k < 8; ++k) { ss0 += v[0][j][k] * v[0][j][k]; ss1 += v[1][j][k] * v[1][j][k]; }
;         const float rs0 = rsqrtf(wave_sum(ss0) * (1.0f / D) + EPS), rs1 = rsqrtf(wave_sum(ss1) * (1.0f / D) + EPS);
;         const float* sh = mod_shift + (size_t)bi * NMOD; const float* sc = mod_scale + (size_t)bi * NMOD;
; #pragma unroll
;         for (int j = 0; j < 4; ++j) { const int c = 8 * lane + 512 * j;
;             const f32x4 s0 = 1.0f + *(const f32x4*)(sc + c), s1 = 1.0f + *(const f32x4*)(sc + c + 4), h0 = *(const f32x4*)(sh + c), h1 = *(const f32x4*)(sh + c + 4);
;             u32x4 w0, w1;
;             w0.x = pk2(v[0][j][0] * rs0 * s0[0] + h0[0], v[0][j][1] * rs0 * s0[1] + h0[1]); w0.y = pk2(v[0][j][2] * rs0 * s0[2] + h0[2], v[0][j][3] * rs0 * s0[3] + h0[3]);
;             w0.z = pk2(v[0][j][4] * rs0 * s1[0] + h1[0], v[0][j][5] * rs0 * s1[1] + h1[1]); w0.w = pk2(v[0][j][6] * rs0 * s1[2] + h1[2], v[0][j][7] * rs0 * s1[3] + h1[3]);
;             w1.x = pk2(v[1][j][0] * rs1 * s0[0] + h0[0], v[1][j][1] * rs1 * s0[1] + h0[1]); w1.y = pk2(v[1][j][2] * rs1 * s0[2] + h0[2], v[1][j][3] * rs1 * s0[3] + h0[3]);
;             w1.z = pk2(v[1][j][4] * rs1 * s1[0] + h1[0], v[1][j][5] * rs1 * s1[1] + h1[1]); w1.w = pk2(v[1][j][6] * rs1 * s1[2] + h1[2], v[1][j][7] * rs1 * s1[3] + h1[3]);
;             *(u32x4*)(XN + (size_t)row0 * D + c) = w0; *(u32x4*)(XN + (size_t)(row0 + 1) * D + c) = w1; }
	v_pk_fma_f32 v[18:19], v[20:21], v[20:21], v[18:19]
	v_mov_b32_e32 v20, v26
	v_pk_fma_f32 v[18:19], v[22:23], v[22:23], v[18:19]
	v_mov_b32_e32 v21, v46
	v_mov_b32_e32 v22, v27
	v_mov_b32_e32 v23, v47
	v_pk_fma_f32 v[18:19], v[20:21], v[20:21], v[18:19]
	v_mov_b32_e32 v28, v24
	v_mov_b32_e32 v29, v44
	v_pk_fma_f32 v[102:103], v[22:23], v[22:23], v[18:19]
	v_mov_b32_e32 v114, v25
	v_mov_b32_e32 v115, v45
	v_pk_fma_f32 v[28:29], v[28:29], v[28:29], v[102:103]
	v_mov_b32_e32 v110, v90
	v_mov_b32_e32 v111, v42
	v_pk_fma_f32 v[28:29], v[114:115], v[114:115], v[28:29]
	v_mov_b32_e32 v112, v91
	v_mov_b32_e32 v113, v43
	v_pk_fma_f32 v[28:29], v[110:111], v[110:111], v[28:29]
	v_lshlrev_b32_e32 v52, 16, v11
	v_and_b32_e32 v53, 0xffff0000, v11
	v_lshlrev_b32_e32 v54, 16, v10
	v_and_b32_e32 v55, 0xffff0000, v10
	v_mov_b32_e32 v10, v88
	v_mov_b32_e32 v11, v40
	v_pk_fma_f32 v[28:29], v[112:113], v[112:113], v[28:29]
	v_lshlrev_b32_e32 v22, 16, v14
	v_mov_b32_e32 v108, v89
	v_mov_b32_e32 v109, v41
	v_pk_fma_f32 v[10:11], v[10:11], v[10:11], v[28:29]
	v_and_b32_e32 v23, 0xffff0000, v14
	v_pk_fma_f32 v[10:11], v[108:109], v[108:109], v[10:11]
	v_mov_b32_e32 v108, v22
	v_mov_b32_e32 v109, v54
	v_lshlrev_b32_e32 v20, 16, v16
	v_and_b32_e32 v21, 0xffff0000, v16
	v_lshlrev_b32_e32 v16, 16, v15
	v_mov_b32_e32 v110, v23
	v_mov_b32_e32 v111, v55
	v_pk_fma_f32 v[10:11], v[108:109], v[108:109], v[10:11]
	v_lshlrev_b32_e32 v18, 16, v17
	v_and_b32_e32 v19, 0xffff0000, v17
	v_and_b32_e32 v17, 0xffff0000, v15
	v_lshlrev_b32_e32 v50, 16, v12
	v_and_b32_e32 v51, 0xffff0000, v12
	v_mov_b32_e32 v28, v16
	v_mov_b32_e32 v29, v52
	v_pk_fma_f32 v[10:11], v[110:111], v[110:111], v[10:11]
	v_pk_mul_f32 v[106:107], v[20:21], v[20:21]
	v_lshlrev_b32_e32 v48, 16, v13
	v_and_b32_e32 v49, 0xffff0000, v13
	v_pk_mul_f32 v[12:13], v[50:51], v[50:51]
	v_mov_b32_e32 v102, v17
	v_mov_b32_e32 v103, v53
	v_pk_fma_f32 v[10:11], v[28:29], v[28:29], v[10:11]
	v_mov_b32_e32 v28, v106
	v_pk_fma_f32 v[10:11], v[102:103], v[102:103], v[10:11]
	v_mov_b32_e32 v29, v12
	v_pk_mul_f32 v[104:105], v[18:19], v[18:19]
	v_pk_mul_f32 v[14:15], v[48:49], v[48:49]
	v_pk_add_f32 v[10:11], v[28:29], v[10:11]
	v_mov_b32_e32 v12, v107
	v_pk_add_f32 v[10:11], v[12:13], v[10:11]
	v_mov_b32_e32 v12, v104
	v_mov_b32_e32 v13, v14
	v_pk_add_f32 v[10:11], v[12:13], v[10:11]
	v_mov_b32_e32 v14, v105
	v_pk_add_f32 v[10:11], v[14:15], v[10:11]
	ds_bpermute_b32 v12, v92, v10
	ds_bpermute_b32 v13, v92, v11
	s_waitcnt lgkmcnt(0)
	v_pk_add_f32 v[10:11], v[10:11], v[12:13]
	ds_bpermute_b32 v12, v93, v10
	ds_bpermute_b32 v13, v93, v11
	s_waitcnt lgkmcnt(0)
	v_pk_add_f32 v[10:11], v[10:11], v[12:13]
	ds_bpermute_b32 v12, v94, v10
	ds_bpermute_b32 v13, v94, v11
	s_waitcnt lgkmcnt(0)
	v_pk_add_f32 v[10:11], v[10:11], v[12:13]
	ds_bpermute_b32 v12, v95, v10
	ds_bpermute_b32 v13, v95, v11
	s_waitcnt lgkmcnt(0)
	v_pk_add_f32 v[10:11], v[10:11], v[12:13]
	ds_bpermute_b32 v12, v96, v10
	ds_bpermute_b32 v13, v96, v11
	s_waitcnt lgkmcnt(0)
	v_pk_add_f32 v[10:11], v[10:11], v[12:13]
	ds_bpermute_b32 v12, v97, v10
	ds_bpermute_b32 v13, v97, v11
	s_waitcnt lgkmcnt(0)
	v_pk_add_f32 v[10:11], v[10:11], v[12:13]
	s_nop 0
	v_pk_fma_f32 v[10:11], v[10:11], s[18:19], v[162:163] op_sel_hi:[1,0,0]
	s_nop 0
	v_mul_f32_e32 v12, 0x4b800000, v10
	v_cmp_gt_f32_e64 s[0:1], s91, v10
	v_cmp_gt_f32_e32 vcc, s91, v11
	s_nop 0
	v_cndmask_b32_e64 v10, v10, v12, s[0:1]
	v_rsq_f32_e32 v10, v10
	s_nop 0
	v_mul_f32_e32 v12, 0x45800000, v10
	v_cndmask_b32_e64 v10, v10, v12, s[0:1]
	v_pk_mul_f32 v[12:13], v[10:11], v[62:63] op_sel_hi:[0,1]
	v_pk_fma_f32 v[12:13], v[0:1], v[12:13], v[6:7]
	v_pk_mul_f32 v[62:63], v[10:11], v[86:87] op_sel_hi:[0,1]
	v_cvt_pk_bf16_f32 v102, v12, v13
	v_pk_mul_f32 v[12:13], v[10:11], v[60:61] op_sel_hi:[0,1]
	v_pk_fma_f32 v[12:13], v[70:71], v[12:13], v[8:9]
	v_pk_mul_f32 v[60:61], v[10:11], v[84:85] op_sel_hi:[0,1]
	v_cvt_pk_bf16_f32 v103, v12, v13
	v_pk_mul_f32 v[12:13], v[10:11], v[58:59] op_sel_hi:[0,1]
	v_pk_fma_f32 v[12:13], v[72:73], v[12:13], v[2:3]
	v_pk_mul_f32 v[58:59], v[10:11], v[82:83] op_sel_hi:[0,1]
	v_cvt_pk_bf16_f32 v104, v12, v13
	v_pk_mul_f32 v[12:13], v[10:11], v[56:57] op_sel_hi:[0,1]
	v_pk_mul_f32 v[56:57], v[10:11], v[64:65] op_sel_hi:[0,1]
	v_mul_f32_e32 v64, 0x4b800000, v11
	v_pk_mul_f32 v[28:29], v[10:11], v[26:27] op_sel_hi:[0,1]
	v_pk_mul_f32 v[26:27], v[10:11], v[24:25] op_sel_hi:[0,1]
	v_pk_mul_f32 v[24:25], v[10:11], v[90:91] op_sel_hi:[0,1]
	v_pk_mul_f32 v[14:15], v[10:11], v[88:89] op_sel_hi:[0,1]
	v_cndmask_b32_e32 v11, v11, v64, vcc
	v_rsq_f32_e32 v11, v11
	v_pk_fma_f32 v[12:13], v[68:69], v[12:13], v[4:5]
	s_mov_b32 s0, 0x11401000
	v_cvt_pk_bf16_f32 v105, v12, v13
	v_mul_f32_e32 v64, 0x45800000, v11
	v_cndmask_b32_e32 v64, v11, v64, vcc
	v_pk_mul_f32 v[80:81], v[64:65], v[80:81] op_sel_hi:[0,1]
	v_pk_fma_f32 v[0:1], v[0:1], v[80:81], v[6:7]
	v_pk_mul_f32 v[6:7], v[64:65], v[78:79] op_sel_hi:[0,1]
	v_pk_fma_f32 v[6:7], v[70:71], v[6:7], v[8:9]
	v_add_co_u32_e64 v12, s[0:1], s0, v66
	v_cvt_pk_bf16_f32 v0, v0, v1
	v_cvt_pk_bf16_f32 v1, v6, v7
	v_pk_mul_f32 v[6:7], v[64:65], v[76:77] op_sel_hi:[0,1]
	v_addc_co_u32_e64 v13, s[0:1], 0, v67, s[0:1]
	v_pk_fma_f32 v[2:3], v[72:73], v[6:7], v[2:3]
	v_pk_mul_f32 v[6:7], v[64:65], v[74:75] op_sel_hi:[0,1]
	v_pk_fma_f32 v[4:5], v[68:69], v[6:7], v[4:5]
	s_mov_b32 s0, 0x11400000
	v_cvt_pk_bf16_f32 v2, v2, v3
	v_cvt_pk_bf16_f32 v3, v4, v5
; __device__ __forceinline__ unsigned pk2(float lo, float hi) { const f32x2 v = {lo, hi}; return __builtin_bit_cast(unsigned, __builtin_convertvector(v, bf16x2_t)); }
; __device__ __forceinline__ void rownorm_phase(const XBuf xin, const float* mod_shift, const float* mod_scale, bf16_t* XN, int lane, int gw, int NGW) {
;     ...
;         for (int j = 0; j < 4; ++j) { const int c = 8 * lane + 512 * j;
;             const f32x4 s0 = 1.0f + *(const f32x4*)(sc + c), s1 = 1.0f + *(const f32x4*)(sc + c + 4), h0 = *(const f32x4*)(sh + c), h1 = *(const f32x4*)(sh + c + 4);
;             u32x4 w0, w1;
;             w0.x = pk2(v[0][j][0] * rs0 * s0[0] + h0[0], v[0][j][1] * rs0 * s0[1] + h0[1]); w0.y = pk2(v[0][j][2] * rs0 * s0[2] + h0[2], v[0][j][3] * rs0 * s0[3] + h0[3]);
;             w0.z = pk2(v[0][j][4] * rs0 * s1[0] + h1[0], v[0][j][5] * rs0 * s1[1] + h1[1]); w0.w = pk2(v[0][j][6] * rs0 * s1[2] + h1[2], v[0][j][7] * rs0 * s1[3] + h1[3]);
;             w1.x = pk2(v[1][j][0] * rs1 * s0[0] + h0[0], v[1][j][1] * rs1 * s0[1] + h0[1]); w1.y = pk2(v[1][j][2] * rs1 * s0[2] + h0[2], v[1][j][3] * rs1 * s0[3] + h0[3]);
;             w1.z = pk2(v[1][j][4] * rs1 * s1[0] + h1[0], v[1][j][5] * rs1 * s1[1] + h1[1]); w1.w = pk2(v[1][j][6] * rs1 * s1[2] + h1[2], v[1][j][7] * rs1 * s1[3] + h1[3]);
;             *(u32x4*)(XN + (size_t)row0 * D + c) = w0; *(u32x4*)(XN + (size_t)(row0 + 1) * D + c) = w1; }
	v_add_co_u32_e32 v4, vcc, s0, v66
	global_store_dwordx4 v[12:13], v[102:105], off
	s_nop 0
	v_addc_co_u32_e32 v5, vcc, 0, v67, vcc
	global_store_dwordx4 v[4:5], v[0:3], off
	v_pk_mul_f32 v[66:67], v[64:65], v[38:39] op_sel_hi:[0,1]
	v_pk_mul_f32 v[68:69], v[64:65], v[36:37] op_sel_hi:[0,1]
	v_pk_mul_f32 v[70:71], v[64:65], v[32:33] op_sel_hi:[0,1]
	v_pk_mul_f32 v[72:73], v[64:65], v[30:31] op_sel_hi:[0,1]
	v_pk_mul_f32 v[38:39], v[64:65], v[46:47] op_sel_hi:[0,1]
	v_pk_mul_f32 v[36:37], v[64:65], v[44:45] op_sel_hi:[0,1]
	v_pk_mul_f32 v[32:33], v[64:65], v[42:43] op_sel_hi:[0,1]
	v_pk_mul_f32 v[30:31], v[64:65], v[40:41] op_sel_hi:[0,1]
	v_mov_b32_e32 v40, v124
	v_mov_b32_e32 v41, v125
	v_mov_b32_e32 v42, v126
	v_mov_b32_e32 v43, v127
	v_mov_b32_e32 v44, v128
	v_mov_b32_e32 v45, v129
	v_mov_b32_e32 v46, v130
	v_mov_b32_e32 v47, v131
	v_pk_mul_f32 v[8:9], v[64:65], v[54:55] op_sel_hi:[0,1]
	v_pk_mul_f32 v[6:7], v[64:65], v[52:53] op_sel_hi:[0,1]
	v_pk_mul_f32 v[2:3], v[64:65], v[50:51] op_sel_hi:[0,1]
	v_pk_mul_f32 v[0:1], v[64:65], v[48:49] op_sel_hi:[0,1]
	v_pk_add_f32 v[64:65], v[42:43], 1.0 op_sel_hi:[1,0]
	v_pk_add_f32 v[52:53], v[46:47], 1.0 op_sel_hi:[1,0]
	v_pk_add_f32 v[54:55], v[44:45], 1.0 op_sel_hi:[1,0]
	v_pk_add_f32 v[74:75], v[40:41], 1.0 op_sel_hi:[1,0]
	v_mov_b32_e32 v40, v132
	v_mov_b32_e32 v41, v133
	v_mov_b32_e32 v42, v134
	v_mov_b32_e32 v43, v135
	v_mov_b32_e32 v44, v136
	v_mov_b32_e32 v45, v137
	v_mov_b32_e32 v46, v138
	v_mov_b32_e32 v47, v139
	v_pk_fma_f32 v[48:49], v[54:55], v[66:67], v[44:45]
	v_pk_fma_f32 v[50:51], v[52:53], v[68:69], v[46:47]
	v_cvt_pk_bf16_f32 v48, v48, v49
	v_cvt_pk_bf16_f32 v49, v50, v51
	v_pk_fma_f32 v[50:51], v[74:75], v[70:71], v[40:41]
	v_pk_fma_f32 v[66:67], v[64:65], v[72:73], v[42:43]
	v_pk_fma_f32 v[44:45], v[54:55], v[62:63], v[44:45]
	v_pk_fma_f32 v[46:47], v[52:53], v[60:61], v[46:47]
	v_pk_fma_f32 v[40:41], v[74:75], v[58:59], v[40:41]
	v_cvt_pk_bf16_f32 v50, v50, v51
	v_cvt_pk_bf16_f32 v51, v66, v67
	v_cvt_pk_bf16_f32 v44, v44, v45
	v_cvt_pk_bf16_f32 v45, v46, v47
	v_cvt_pk_bf16_f32 v46, v40, v41
	v_pk_fma_f32 v[40:41], v[64:65], v[56:57], v[42:43]
	s_nop 0
	v_cvt_pk_bf16_f32 v47, v40, v41
	global_store_dwordx4 v[4:5], v[48:51], off offset:1024
	global_store_dwordx4 v[12:13], v[44:47], off offset:1024
	s_nop 1
	v_mov_b32_e32 v40, v140
	v_mov_b32_e32 v41, v141
	v_mov_b32_e32 v42, v142
	v_mov_b32_e32 v43, v143
	s_nop 0
	s_nop 1
	v_mov_b32_e32 v44, v144
	v_mov_b32_e32 v45, v145
	v_mov_b32_e32 v46, v146
	v_mov_b32_e32 v47, v147
	v_pk_add_f32 v[56:57], v[42:43], 1.0 op_sel_hi:[1,0]
	v_pk_add_f32 v[52:53], v[46:47], 1.0 op_sel_hi:[1,0]
	v_pk_add_f32 v[54:55], v[44:45], 1.0 op_sel_hi:[1,0]
	v_pk_add_f32 v[58:59], v[40:41], 1.0 op_sel_hi:[1,0]
	v_mov_b32_e32 v40, v148
	v_mov_b32_e32 v41, v149
	v_mov_b32_e32 v42, v150
	v_mov_b32_e32 v43, v151
	v_mov_b32_e32 v44, v152
	v_mov_b32_e32 v45, v153
	v_mov_b32_e32 v46, v154
	v_mov_b32_e32 v47, v155
	v_pk_fma_f32 v[32:33], v[58:59], v[32:33], v[40:41]
	v_pk_fma_f32 v[38:39], v[54:55], v[38:39], v[44:45]
	v_pk_fma_f32 v[36:37], v[52:53], v[36:37], v[46:47]
	v_pk_fma_f32 v[30:31], v[56:57], v[30:31], v[42:43]
	v_cvt_pk_bf16_f32 v48, v38, v39
	v_cvt_pk_bf16_f32 v49, v36, v37
	v_cvt_pk_bf16_f32 v50, v32, v33
	v_cvt_pk_bf16_f32 v51, v30, v31
	v_pk_fma_f32 v[28:29], v[54:55], v[28:29], v[44:45]
	v_pk_fma_f32 v[26:27], v[52:53], v[26:27], v[46:47]
	v_pk_fma_f32 v[24:25], v[58:59], v[24:25], v[40:41]
	v_pk_fma_f32 v[14:15], v[56:57], v[14:15], v[42:43]
	v_cvt_pk_bf16_f32 v28, v28, v29
	v_cvt_pk_bf16_f32 v29, v26, v27
	v_cvt_pk_bf16_f32 v30, v24, v25
	v_cvt_pk_bf16_f32 v31, v14, v15
	global_store_dwordx4 v[4:5], v[48:51], off offset:2048
	global_store_dwordx4 v[12:13], v[28:31], off offset:2048
	s_nop 1
	v_mov_b32_e32 v24, v156
	v_mov_b32_e32 v25, v157
	v_mov_b32_e32 v26, v158
	v_mov_b32_e32 v27, v159
	s_nop 0
	s_nop 1
	v_mov_b32_e32 v28, v168
	v_mov_b32_e32 v29, v169
	v_mov_b32_e32 v30, v170
	v_mov_b32_e32 v31, v171
	v_pk_add_f32 v[40:41], v[26:27], 1.0 op_sel_hi:[1,0]
	v_pk_add_f32 v[14:15], v[30:31], 1.0 op_sel_hi:[1,0]
	v_pk_add_f32 v[32:33], v[28:29], 1.0 op_sel_hi:[1,0]
	v_pk_add_f32 v[42:43], v[24:25], 1.0 op_sel_hi:[1,0]
	v_mov_b32_e32 v24, v172
	v_mov_b32_e32 v25, v173
	v_mov_b32_e32 v26, v174
	v_mov_b32_e32 v27, v175
	v_mov_b32_e32 v28, v176
	v_mov_b32_e32 v29, v177
	v_mov_b32_e32 v30, v178
	v_mov_b32_e32 v31, v179
	v_pk_fma_f32 v[2:3], v[42:43], v[2:3], v[24:25]
	v_pk_fma_f32 v[0:1], v[40:41], v[0:1], v[26:27]
	v_cvt_pk_bf16_f32 v38, v2, v3
	v_cvt_pk_bf16_f32 v39, v0, v1
	v_pk_mul_f32 v[0:1], v[10:11], v[22:23] op_sel_hi:[0,1]
	v_pk_mul_f32 v[2:3], v[10:11], v[16:17] op_sel_hi:[0,1]
	v_pk_fma_f32 v[6:7], v[14:15], v[6:7], v[30:31]
	v_pk_fma_f32 v[0:1], v[32:33], v[0:1], v[28:29]
	v_pk_fma_f32 v[2:3], v[14:15], v[2:3], v[30:31]
	v_pk_fma_f32 v[8:9], v[32:33], v[8:9], v[28:29]
	v_cvt_pk_bf16_f32 v37, v6, v7
	v_cvt_pk_bf16_f32 v0, v0, v1
	v_cvt_pk_bf16_f32 v1, v2, v3
	v_pk_mul_f32 v[2:3], v[10:11], v[20:21] op_sel_hi:[0,1]
	v_pk_mul_f32 v[6:7], v[10:11], v[18:19] op_sel_hi:[0,1]
	v_cvt_pk_bf16_f32 v36, v8, v9
	v_pk_fma_f32 v[2:3], v[42:43], v[2:3], v[24:25]
	v_pk_fma_f32 v[6:7], v[40:41], v[6:7], v[26:27]
	v_cvt_pk_bf16_f32 v2, v2, v3
	v_cvt_pk_bf16_f32 v3, v6, v7
	global_store_dwordx4 v[4:5], v[36:39], off offset:3072
	global_store_dwordx4 v[12:13], v[0:3], off offset:3072
	s_cbranch_scc0 .LBB0_514

; __device__ __forceinline__ void rownorm_phase(const XBuf xin, const float* mod_shift, const float* mod_scale, bf16_t* XN, int lane, int gw, int NGW) {
;     ...
;         for (int j = 0; j < 4; ++j)
; #pragma unroll
;             for (int k = 0; k < 8; ++k) { ss0 += v[0][j][k] * v[0][j][k]; ss1 += v[1][j][k] * v[1][j][k]; }
;         const float rs0 = rsqrtf(wave_sum(ss0) * (1.0f / D) + EPS), rs1 = rsqrtf(wave_sum(ss1) * (1.0f / D) + EPS);
;         const float* sh = mod_shift + (size_t)bi * NMOD; const float* sc = mod_scale + (size_t)bi * NMOD;
; #pragma unroll
;         for (int j = 0; j < 4; ++j) { const int c = 8 * lane + 512 * j;
;             const f32x4 s0 = 1.0f + *(const f32x4*)(sc + c), s1 = 1.0f + *(const f32x4*)(sc + c + 4), h0 = *(const f32x4*)(sh + c), h1 = *(const f32x4*)(sh + c + 4);
.Lrn0_skip:
	v_mov_b32_e32 v90, v12
	v_mov_b32_e32 v91, v4
	v_pk_mul_f32 v[90:91], v[90:91], v[90:91]
	v_mov_b32_e32 v92, v13
	v_mov_b32_e32 v93, v5
	v_pk_fma_f32 v[90:91], v[92:93], v[92:93], v[90:91]
	v_mov_b32_e32 v92, v14
	v_mov_b32_e32 v93, v6
	v_pk_fma_f32 v[90:91], v[92:93], v[92:93], v[90:91]
	v_mov_b32_e32 v92, v15
	v_mov_b32_e32 v93, v7
	v_pk_fma_f32 v[90:91], v[92:93], v[92:93], v[90:91]
	v_mov_b32_e32 v92, v8
	v_mov_b32_e32 v93, v0
	v_pk_fma_f32 v[90:91], v[92:93], v[92:93], v[90:91]
	v_mov_b32_e32 v92, v9
	v_mov_b32_e32 v93, v1
	v_pk_fma_f32 v[90:91], v[92:93], v[92:93], v[90:91]
	v_mov_b32_e32 v92, v10
	v_mov_b32_e32 v93, v2
	v_pk_fma_f32 v[90:91], v[92:93], v[92:93], v[90:91]
	v_mov_b32_e32 v92, v11
	v_mov_b32_e32 v93, v3
	v_pk_fma_f32 v[90:91], v[92:93], v[92:93], v[90:91]
	v_mov_b32_e32 v92, v28
	v_mov_b32_e32 v93, v20
	v_pk_fma_f32 v[90:91], v[92:93], v[92:93], v[90:91]
	v_mov_b32_e32 v92, v29
	v_mov_b32_e32 v93, v21
	v_pk_fma_f32 v[90:91], v[92:93], v[92:93], v[90:91]
	v_mov_b32_e32 v92, v30
	v_mov_b32_e32 v93, v22
	v_pk_fma_f32 v[90:91], v[92:93], v[92:93], v[90:91]
	v_mov_b32_e32 v92, v31
	v_mov_b32_e32 v93, v23
	v_pk_fma_f32 v[90:91], v[92:93], v[92:93], v[90:91]
	v_mov_b32_e32 v92, v24
	v_mov_b32_e32 v93, v16
	v_pk_fma_f32 v[90:91], v[92:93], v[92:93], v[90:91]
	v_mov_b32_e32 v92, v25
	v_mov_b32_e32 v93, v17
	v_pk_fma_f32 v[90:91], v[92:93], v[92:93], v[90:91]
	v_mov_b32_e32 v92, v26
	v_mov_b32_e32 v93, v18
	s_add_i32 s0, s4, 0xffff8000
	v_pk_fma_f32 v[90:91], v[92:93], v[92:93], v[90:91]
	v_mov_b32_e32 v92, v27
	v_mov_b32_e32 v93, v19
	s_lshr_b32 s0, s0, 6
	v_pk_fma_f32 v[90:91], v[92:93], v[92:93], v[90:91]
	v_mov_b32_e32 v92, v44
	v_mov_b32_e32 v93, v36
	s_add_i32 s0, s0, 2
	s_ashr_i32 s1, s4, 14
	v_pk_fma_f32 v[90:91], v[92:93], v[92:93], v[90:91]
	v_mov_b32_e32 v92, v45
	v_mov_b32_e32 v93, v37
	s_cmp_lt_i32 s4, 0x8000
	v_pk_fma_f32 v[90:91], v[92:93], v[92:93], v[90:91]
	v_mov_b32_e32 v92, v46
	v_mov_b32_e32 v93, v38
	v_pk_fma_f32 v[90:91], v[92:93], v[92:93], v[90:91]
	v_mov_b32_e32 v92, v47
	v_mov_b32_e32 v93, v39
	s_cselect_b32 s0, s1, s0
	v_pk_fma_f32 v[90:91], v[92:93], v[92:93], v[90:91]
	v_mov_b32_e32 v92, v40
	v_mov_b32_e32 v93, v32
	s_mul_hi_i32 s1, s0, 0xc000
	s_mul_i32 s0, s0, 0xc000
	v_readlane_b32 s2, v254, 22
	v_pk_fma_f32 v[90:91], v[92:93], v[92:93], v[90:91]
	v_mov_b32_e32 v92, v41
	v_mov_b32_e32 v93, v33
	s_add_u32 s12, s2, s0
	v_readlane_b32 s2, v254, 23
	v_pk_fma_f32 v[90:91], v[92:93], v[92:93], v[90:91]
	v_mov_b32_e32 v92, v42
	v_mov_b32_e32 v93, v34
	s_addc_u32 s13, s2, s1
	v_pk_fma_f32 v[90:91], v[92:93], v[92:93], v[90:91]
	v_mov_b32_e32 v92, v43
	v_mov_b32_e32 v93, v35
	s_add_u32 s14, s16, s0
	v_pk_fma_f32 v[90:91], v[92:93], v[92:93], v[90:91]
	v_mov_b32_e32 v92, v56
	v_mov_b32_e32 v93, v48
	s_addc_u32 s15, s17, s1
	v_pk_fma_f32 v[98:99], v[92:93], v[92:93], v[90:91]
	global_load_dwordx4 v[90:93], v86, s[14:15] offset:16
	global_load_dwordx4 v[94:97], v86, s[14:15]
	v_mov_b32_e32 v100, v57
	v_mov_b32_e32 v101, v49
	v_pk_fma_f32 v[110:111], v[100:101], v[100:101], v[98:99]
	global_load_dwordx4 v[98:101], v86, s[12:13] offset:16
	global_load_dwordx4 v[102:105], v86, s[12:13]
	global_load_dwordx4 v[116:119], v86, s[14:15] offset:2048
	global_load_dwordx4 v[120:123], v86, s[14:15] offset:2064
	global_load_dwordx4 v[124:127], v86, s[12:13] offset:2048
	global_load_dwordx4 v[128:131], v86, s[12:13] offset:2064
	global_load_dwordx4 v[132:135], v87, s[14:15]
	global_load_dwordx4 v[136:139], v87, s[14:15] offset:16
	global_load_dwordx4 v[140:143], v87, s[12:13]
	global_load_dwordx4 v[144:147], v87, s[12:13] offset:16
	global_load_dwordx4 v[148:151], v88, s[14:15]
	global_load_dwordx4 v[152:155], v88, s[14:15] offset:16
	global_load_dwordx4 v[156:159], v88, s[12:13]
	global_load_dwordx4 v[168:171], v88, s[12:13] offset:16
	v_mov_b32_e32 v112, v58
	v_mov_b32_e32 v113, v50
	v_pk_mul_f32 v[106:107], v[52:53], v[52:53]
	v_pk_mul_f32 v[108:109], v[60:61], v[60:61]
	v_pk_fma_f32 v[110:111], v[112:113], v[112:113], v[110:111]
	v_mov_b32_e32 v112, v59
	v_mov_b32_e32 v113, v51
	v_pk_fma_f32 v[110:111], v[112:113], v[112:113], v[110:111]
	v_mov_b32_e32 v112, v108
	v_mov_b32_e32 v113, v106
	v_pk_add_f32 v[110:111], v[112:113], v[110:111]
	v_pk_mul_f32 v[112:113], v[54:55], v[54:55]
	v_pk_mul_f32 v[114:115], v[62:63], v[62:63]
	v_mov_b32_e32 v106, v109
	v_pk_add_f32 v[106:107], v[106:107], v[110:111]
	v_mov_b32_e32 v108, v114
	v_mov_b32_e32 v109, v112
	v_pk_add_f32 v[106:107], v[108:109], v[106:107]
	v_mov_b32_e32 v112, v115
	v_pk_add_f32 v[106:107], v[112:113], v[106:107]
	ds_bpermute_b32 v109, v80, v107
	ds_bpermute_b32 v108, v80, v106
	s_mov_b32 s0, 0x3a000000
	s_add_i32 s4, s4, s6
	s_add_u32 s10, s10, s6
	s_addc_u32 s11, s11, s7
	s_waitcnt lgkmcnt(0)
	v_pk_add_f32 v[106:107], v[106:107], v[108:109]
	ds_bpermute_b32 v109, v81, v107
	ds_bpermute_b32 v108, v81, v106
	s_cmp_gt_i32 s4, 0x87ff
	s_waitcnt lgkmcnt(0)
	v_pk_add_f32 v[106:107], v[106:107], v[108:109]
	ds_bpermute_b32 v109, v82, v107
	ds_bpermute_b32 v108, v82, v106
	s_waitcnt lgkmcnt(0)
	v_pk_add_f32 v[106:107], v[106:107], v[108:109]
	ds_bpermute_b32 v109, v83, v107
	ds_bpermute_b32 v108, v83, v106
	s_waitcnt lgkmcnt(0)
	v_pk_add_f32 v[106:107], v[106:107], v[108:109]
	ds_bpermute_b32 v109, v84, v107
	ds_bpermute_b32 v108, v84, v106
	s_waitcnt lgkmcnt(0)
	v_pk_add_f32 v[106:107], v[106:107], v[108:109]
	ds_bpermute_b32 v109, v85, v107
	ds_bpermute_b32 v108, v85, v106
	s_waitcnt lgkmcnt(0)
	v_pk_add_f32 v[106:107], v[106:107], v[108:109]
	s_nop 0
	v_pk_fma_f32 v[106:107], v[106:107], s[0:1], v[162:163] op_sel_hi:[1,0,0]
	s_waitcnt vmcnt(0)
; __device__ __forceinline__ unsigned pk2(float lo, float hi) { const f32x2 v = {lo, hi}; return __builtin_bit_cast(unsigned, __builtin_convertvector(v, bf16x2_t)); }
; __device__ __forceinline__ void rownorm_phase(const XBuf xin, const float* mod_shift, const float* mod_scale, bf16_t* XN, int lane, int gw, int NGW) {
;     ...
;         const float rs0 = rsqrtf(wave_sum(ss0) * (1.0f / D) + EPS), rs1 = rsqrtf(wave_sum(ss1) * (1.0f / D) + EPS);
;         const float* sh = mod_shift + (size_t)bi * NMOD; const float* sc = mod_scale + (size_t)bi * NMOD;
; #pragma unroll
;         for (int j = 0; j < 4; ++j) { const int c = 8 * lane + 512 * j;
;             const f32x4 s0 = 1.0f + *(const f32x4*)(sc + c), s1 = 1.0f + *(const f32x4*)(sc + c + 4), h0 = *(const f32x4*)(sh + c), h1 = *(const f32x4*)(sh + c + 4);
;             u32x4 w0, w1;
;             w0.x = pk2(v[0][j][0] * rs0 * s0[0] + h0[0], v[0][j][1] * rs0 * s0[1] + h0[1]); w0.y = pk2(v[0][j][2] * rs0 * s0[2] + h0[2], v[0][j][3] * rs0 * s0[3] + h0[3]);
;             w0.z = pk2(v[0][j][4] * rs0 * s1[0] + h1[0], v[0][j][5] * rs0 * s1[1] + h1[1]); w0.w = pk2(v[0][j][6] * rs0 * s1[2] + h1[2], v[0][j][7] * rs0 * s1[3] + h1[3]);
;             w1.x = pk2(v[1][j][0] * rs1 * s0[0] + h0[0], v[1][j][1] * rs1 * s0[1] + h0[1]); w1.y = pk2(v[1][j][2] * rs1 * s0[2] + h0[2], v[1][j][3] * rs1 * s0[3] + h0[3]);
;             w1.z = pk2(v[1][j][4] * rs1 * s1[0] + h1[0], v[1][j][5] * rs1 * s1[1] + h1[1]); w1.w = pk2(v[1][j][6] * rs1 * s1[2] + h1[2], v[1][j][7] * rs1 * s1[3] + h1[3]);
;             *(u32x4*)(XN + (size_t)row0 * D + c) = w0; *(u32x4*)(XN + (size_t)(row0 + 1) * D + c) = w1; }
	v_pk_add_f32 v[90:91], v[90:91], 1.0 op_sel_hi:[1,0]
	v_mul_f32_e32 v89, 0x4b800000, v107
	v_cmp_gt_f32_e32 vcc, s91, v107
	v_cmp_gt_f32_e64 s[0:1], s91, v106
	v_pk_add_f32 v[96:97], v[96:97], 1.0 op_sel_hi:[1,0]
	v_cndmask_b32_e32 v89, v107, v89, vcc
	v_rsq_f32_e32 v89, v89
	v_mul_f32_e32 v107, 0x4b800000, v106
	v_cndmask_b32_e64 v106, v106, v107, s[0:1]
	v_rsq_f32_e32 v107, v106
	v_mul_f32_e32 v106, 0x45800000, v89
	v_cndmask_b32_e32 v106, v89, v106, vcc
	v_pk_add_f32 v[94:95], v[94:95], 1.0 op_sel_hi:[1,0]
	v_pk_mul_f32 v[4:5], v[4:5], v[106:107] op_sel_hi:[1,0]
	v_pk_mul_f32 v[6:7], v[6:7], v[106:107] op_sel_hi:[1,0]
	v_pk_mul_f32 v[0:1], v[0:1], v[106:107] op_sel_hi:[1,0]
	v_pk_fma_f32 v[4:5], v[94:95], v[4:5], v[102:103]
	v_pk_fma_f32 v[6:7], v[96:97], v[6:7], v[104:105]
	v_pk_fma_f32 v[0:1], v[90:91], v[0:1], v[98:99]
	v_mul_f32_e32 v89, 0x45800000, v107
	v_pk_add_f32 v[92:93], v[92:93], 1.0 op_sel_hi:[1,0]
	v_cvt_pk_bf16_f32 v4, v4, v5
	v_cvt_pk_bf16_f32 v5, v6, v7
	v_cvt_pk_bf16_f32 v6, v0, v1
	v_pk_mul_f32 v[0:1], v[2:3], v[106:107] op_sel_hi:[1,0]
	v_cndmask_b32_e64 v108, v107, v89, s[0:1]
	v_pk_fma_f32 v[0:1], v[92:93], v[0:1], v[100:101]
	v_pk_mul_f32 v[2:3], v[14:15], v[108:109] op_sel_hi:[1,0]
	v_cvt_pk_bf16_f32 v7, v0, v1
	v_pk_mul_f32 v[0:1], v[12:13], v[108:109] op_sel_hi:[1,0]
	v_pk_fma_f32 v[2:3], v[96:97], v[2:3], v[104:105]
	v_pk_fma_f32 v[0:1], v[94:95], v[0:1], v[102:103]
	s_movk_i32 s0, 0xf000
	v_cvt_pk_bf16_f32 v0, v0, v1
	v_cvt_pk_bf16_f32 v1, v2, v3
	v_pk_mul_f32 v[2:3], v[8:9], v[108:109] op_sel_hi:[1,0]
	v_pk_mul_f32 v[8:9], v[10:11], v[108:109] op_sel_hi:[1,0]
	v_pk_fma_f32 v[2:3], v[90:91], v[2:3], v[98:99]
	v_add_co_u32_e32 v90, vcc, s0, v78
	v_pk_fma_f32 v[8:9], v[92:93], v[8:9], v[100:101]
	s_nop 0
	v_addc_co_u32_e32 v91, vcc, -1, v79, vcc
	v_cvt_pk_bf16_f32 v2, v2, v3
	v_cvt_pk_bf16_f32 v3, v8, v9
	global_store_dwordx4 v[90:91], v[4:7], off offset:-3072
	global_store_dwordx4 v[78:79], v[0:3], off offset:-3072
	s_nop 1
	v_mov_b32_e32 v0, v116
	v_mov_b32_e32 v1, v117
	v_mov_b32_e32 v2, v118
	v_mov_b32_e32 v3, v119
	s_nop 0
	s_nop 1
	v_mov_b32_e32 v4, v120
	v_mov_b32_e32 v5, v121
	v_mov_b32_e32 v6, v122
	v_mov_b32_e32 v7, v123
	v_mov_b32_e32 v8, v124
	v_mov_b32_e32 v9, v125
	v_mov_b32_e32 v10, v126
	v_mov_b32_e32 v11, v127
	v_mov_b32_e32 v12, v128
	v_mov_b32_e32 v13, v129
	v_mov_b32_e32 v14, v130
	v_mov_b32_e32 v15, v131
	v_pk_add_f32 v[92:93], v[2:3], 1.0 op_sel_hi:[1,0]
	v_pk_add_f32 v[94:95], v[0:1], 1.0 op_sel_hi:[1,0]
	v_pk_mul_f32 v[0:1], v[20:21], v[106:107] op_sel_hi:[1,0]
	v_pk_mul_f32 v[2:3], v[22:23], v[106:107] op_sel_hi:[1,0]
	v_pk_fma_f32 v[0:1], v[0:1], v[94:95], v[8:9]
	v_pk_fma_f32 v[2:3], v[2:3], v[92:93], v[10:11]
	v_pk_add_f32 v[96:97], v[6:7], 1.0 op_sel_hi:[1,0]
	v_pk_add_f32 v[6:7], v[4:5], 1.0 op_sel_hi:[1,0]
	v_cvt_pk_bf16_f32 v0, v0, v1
	v_cvt_pk_bf16_f32 v1, v2, v3
	v_pk_mul_f32 v[2:3], v[16:17], v[106:107] op_sel_hi:[1,0]
	v_pk_mul_f32 v[4:5], v[18:19], v[106:107] op_sel_hi:[1,0]
	v_pk_fma_f32 v[2:3], v[2:3], v[6:7], v[12:13]
	v_pk_fma_f32 v[4:5], v[4:5], v[96:97], v[14:15]
	v_cvt_pk_bf16_f32 v2, v2, v3
	v_cvt_pk_bf16_f32 v3, v4, v5
	v_pk_mul_f32 v[4:5], v[28:29], v[108:109] op_sel_hi:[1,0]
	v_pk_mul_f32 v[16:17], v[36:37], v[106:107] op_sel_hi:[1,0]
	v_pk_fma_f32 v[4:5], v[94:95], v[4:5], v[8:9]
	v_pk_mul_f32 v[8:9], v[30:31], v[108:109] op_sel_hi:[1,0]
	v_cvt_pk_bf16_f32 v4, v4, v5
	v_pk_fma_f32 v[8:9], v[92:93], v[8:9], v[10:11]
	v_pk_mul_f32 v[18:19], v[38:39], v[106:107] op_sel_hi:[1,0]
	v_cvt_pk_bf16_f32 v5, v8, v9
	v_pk_mul_f32 v[8:9], v[24:25], v[108:109] op_sel_hi:[1,0]
	v_pk_mul_f32 v[20:21], v[32:33], v[106:107] op_sel_hi:[1,0]
	v_pk_fma_f32 v[6:7], v[6:7], v[8:9], v[12:13]
	v_pk_mul_f32 v[8:9], v[26:27], v[108:109] op_sel_hi:[1,0]
	v_cvt_pk_bf16_f32 v6, v6, v7
; __device__ __forceinline__ unsigned pk2(float lo, float hi) { const f32x2 v = {lo, hi}; return __builtin_bit_cast(unsigned, __builtin_convertvector(v, bf16x2_t)); }
; __device__ __forceinline__ void rownorm_phase(const XBuf xin, const float* mod_shift, const float* mod_scale, bf16_t* XN, int lane, int gw, int NGW) {
;     ...
;         for (int j = 0; j < 4; ++j) { const int c = 8 * lane + 512 * j;
;             const f32x4 s0 = 1.0f + *(const f32x4*)(sc + c), s1 = 1.0f + *(const f32x4*)(sc + c + 4), h0 = *(const f32x4*)(sh + c), h1 = *(const f32x4*)(sh + c + 4);
;             u32x4 w0, w1;
;             w0.x = pk2(v[0][j][0] * rs0 * s0[0] + h0[0], v[0][j][1] * rs0 * s0[1] + h0[1]); w0.y = pk2(v[0][j][2] * rs0 * s0[2] + h0[2], v[0][j][3] * rs0 * s0[3] + h0[3]);
;             w0.z = pk2(v[0][j][4] * rs0 * s1[0] + h1[0], v[0][j][5] * rs0 * s1[1] + h1[1]); w0.w = pk2(v[0][j][6] * rs0 * s1[2] + h1[2], v[0][j][7] * rs0 * s1[3] + h1[3]);
;             w1.x = pk2(v[1][j][0] * rs1 * s0[0] + h0[0], v[1][j][1] * rs1 * s0[1] + h0[1]); w1.y = pk2(v[1][j][2] * rs1 * s0[2] + h0[2], v[1][j][3] * rs1 * s0[3] + h0[3]);
;             w1.z = pk2(v[1][j][4] * rs1 * s1[0] + h1[0], v[1][j][5] * rs1 * s1[1] + h1[1]); w1.w = pk2(v[1][j][6] * rs1 * s1[2] + h1[2], v[1][j][7] * rs1 * s1[3] + h1[3]);
;             *(u32x4*)(XN + (size_t)row0 * D + c) = w0; *(u32x4*)(XN + (size_t)(row0 + 1) * D + c) = w1; }
	v_pk_fma_f32 v[8:9], v[96:97], v[8:9], v[14:15]
	v_pk_mul_f32 v[22:23], v[34:35], v[106:107] op_sel_hi:[1,0]
	v_cvt_pk_bf16_f32 v7, v8, v9
	global_store_dwordx4 v[90:91], v[0:3], off offset:-2048
	global_store_dwordx4 v[78:79], v[4:7], off offset:-2048
	s_nop 1
	v_mov_b32_e32 v0, v132
	v_mov_b32_e32 v1, v133
	v_mov_b32_e32 v2, v134
	v_mov_b32_e32 v3, v135
	s_nop 0
	s_nop 1
	v_mov_b32_e32 v4, v136
	v_mov_b32_e32 v5, v137
	v_mov_b32_e32 v6, v138
	v_mov_b32_e32 v7, v139
	v_mov_b32_e32 v8, v140
	v_mov_b32_e32 v9, v141
	v_mov_b32_e32 v10, v142
	v_mov_b32_e32 v11, v143
	v_mov_b32_e32 v12, v144
	v_mov_b32_e32 v13, v145
	v_mov_b32_e32 v14, v146
	v_mov_b32_e32 v15, v147
	v_pk_mul_f32 v[24:25], v[44:45], v[108:109] op_sel_hi:[1,0]
	v_pk_mul_f32 v[26:27], v[46:47], v[108:109] op_sel_hi:[1,0]
	v_pk_mul_f32 v[28:29], v[40:41], v[108:109] op_sel_hi:[1,0]
	v_pk_mul_f32 v[30:31], v[42:43], v[108:109] op_sel_hi:[1,0]
	v_pk_add_f32 v[2:3], v[2:3], 1.0 op_sel_hi:[1,0]
	v_pk_add_f32 v[0:1], v[0:1], 1.0 op_sel_hi:[1,0]
	v_pk_add_f32 v[6:7], v[6:7], 1.0 op_sel_hi:[1,0]
	v_pk_add_f32 v[4:5], v[4:5], 1.0 op_sel_hi:[1,0]
	v_pk_fma_f32 v[16:17], v[16:17], v[0:1], v[8:9]
	v_pk_fma_f32 v[18:19], v[18:19], v[2:3], v[10:11]
	v_pk_fma_f32 v[20:21], v[20:21], v[4:5], v[12:13]
	v_pk_fma_f32 v[22:23], v[22:23], v[6:7], v[14:15]
	v_pk_fma_f32 v[8:9], v[24:25], v[0:1], v[8:9]
	v_pk_fma_f32 v[10:11], v[26:27], v[2:3], v[10:11]
	v_pk_fma_f32 v[12:13], v[28:29], v[4:5], v[12:13]
	v_pk_fma_f32 v[14:15], v[30:31], v[6:7], v[14:15]
	v_cvt_pk_bf16_f32 v0, v16, v17
	v_cvt_pk_bf16_f32 v1, v18, v19
	v_cvt_pk_bf16_f32 v2, v20, v21
	v_cvt_pk_bf16_f32 v3, v22, v23
	v_cvt_pk_bf16_f32 v4, v8, v9
	v_cvt_pk_bf16_f32 v5, v10, v11
	v_cvt_pk_bf16_f32 v6, v12, v13
	v_cvt_pk_bf16_f32 v7, v14, v15
	global_store_dwordx4 v[90:91], v[0:3], off offset:-1024
	global_store_dwordx4 v[78:79], v[4:7], off offset:-1024
	s_nop 1
	v_mov_b32_e32 v0, v148
	v_mov_b32_e32 v1, v149
	v_mov_b32_e32 v2, v150
	v_mov_b32_e32 v3, v151
	s_nop 0
	s_nop 1
	v_mov_b32_e32 v4, v152
	v_mov_b32_e32 v5, v153
	v_mov_b32_e32 v6, v154
	v_mov_b32_e32 v7, v155
	v_mov_b32_e32 v8, v156
	v_mov_b32_e32 v9, v157
	v_mov_b32_e32 v10, v158
	v_mov_b32_e32 v11, v159
	v_mov_b32_e32 v12, v168
	v_mov_b32_e32 v13, v169
	v_mov_b32_e32 v14, v170
	v_mov_b32_e32 v15, v171
	v_pk_mul_f32 v[16:17], v[48:49], v[106:107] op_sel_hi:[1,0]
	v_pk_mul_f32 v[18:19], v[50:51], v[106:107] op_sel_hi:[1,0]
	v_pk_mul_f32 v[20:21], v[52:53], v[106:107] op_sel_hi:[1,0]
	v_pk_mul_f32 v[22:23], v[54:55], v[106:107] op_sel_hi:[1,0]
	v_pk_mul_f32 v[24:25], v[56:57], v[108:109] op_sel_hi:[1,0]
	v_pk_mul_f32 v[26:27], v[58:59], v[108:109] op_sel_hi:[1,0]
	v_pk_mul_f32 v[28:29], v[60:61], v[108:109] op_sel_hi:[1,0]
	v_pk_mul_f32 v[30:31], v[62:63], v[108:109] op_sel_hi:[1,0]
	v_pk_add_f32 v[2:3], v[2:3], 1.0 op_sel_hi:[1,0]
	v_pk_add_f32 v[0:1], v[0:1], 1.0 op_sel_hi:[1,0]
	v_pk_add_f32 v[6:7], v[6:7], 1.0 op_sel_hi:[1,0]
	v_pk_add_f32 v[4:5], v[4:5], 1.0 op_sel_hi:[1,0]
	v_pk_fma_f32 v[16:17], v[16:17], v[0:1], v[8:9]
	v_pk_fma_f32 v[18:19], v[18:19], v[2:3], v[10:11]
	v_pk_fma_f32 v[20:21], v[20:21], v[4:5], v[12:13]
	v_pk_fma_f32 v[22:23], v[22:23], v[6:7], v[14:15]
	v_pk_fma_f32 v[8:9], v[24:25], v[0:1], v[8:9]
	v_pk_fma_f32 v[10:11], v[26:27], v[2:3], v[10:11]
	v_pk_fma_f32 v[12:13], v[28:29], v[4:5], v[12:13]
	v_pk_fma_f32 v[14:15], v[30:31], v[6:7], v[14:15]
	v_cvt_pk_bf16_f32 v0, v16, v17
	v_cvt_pk_bf16_f32 v1, v18, v19
	v_cvt_pk_bf16_f32 v2, v20, v21
	v_cvt_pk_bf16_f32 v3, v22, v23
	v_cvt_pk_bf16_f32 v4, v8, v9
	v_cvt_pk_bf16_f32 v5, v10, v11
	v_cvt_pk_bf16_f32 v6, v12, v13
	v_cvt_pk_bf16_f32 v7, v14, v15
	global_store_dwordx4 v[78:79], v[0:3], off offset:-4096
	global_store_dwordx4 v[78:79], v[4:7], off
	v_lshl_add_u64 v[78:79], v[78:79], 0, s[8:9]
	s_cbranch_scc1 .LBB0_829
